# attention: q-blocks 0 and 1 swapped between the even and odd CU of a pair (84/60+33 -> 80/64+33 tile steps); GEMM accumulator zeroing with v_mov_b64
# speedup vs baseline: 1.0060x; 1.0032x over previous
;     __host__ __device__ bool next(int i, Unit& u) const { const long L = (long)i * G + c; if (L >= nwg) return false; const int l = (int)L; u.ks = l % nS; const int t = l / nS; u.pn = t % nN; u.pm = t / nN; return true; }
; template <class Epi, class Sched, bool ALIGN_EPI = false, bool SP2 = false>
; __device__ __forceinline__ void gemm_phase(PG8_LAS unsigned char* lds, const Gemm g, const Sched& S, const Epi& E) {
;     ...
;         const bool has_next = S.next(ui + 1, nxt);
;         const char* nA = has_next ? (const char*)g.A + (size_t)nxt.pm * tstepA + (size_t)nxt.ks * ksl : cA; const char* nB = has_next ? (const char*)g.Bt + (size_t)nxt.pn * tstepB + (size_t)nxt.ks * ksl : cB;
;     ...
;         for (int a = 0; a < 2; ++a)
; #pragma unroll
;             for (int b = 0; b < 2; ++b)
; #pragma unroll
;                 for (int m = 0; m < 4; ++m)
; #pragma unroll
;                     for (int n = 0; n < 2; ++n) acc[a][b][m][n] = (f32x4){0.f, 0.f, 0.f, 0.f};
.LBB0_453:
	s_ashr_i32 s73, s72, 31
	s_lshl_b64 s[0:1], s[72:73], 19
	s_add_u32 s74, s54, s0
	s_addc_u32 s75, s55, s1
	s_and_b64 s[0:1], s[38:39], exec
	s_cselect_b32 s2, s75, s49
	s_cselect_b32 s3, s74, s48
	s_ashr_i32 s71, s70, 31
	s_lshl_b64 s[0:1], s[70:71], 19
	s_add_u32 s76, s56, s0
	s_addc_u32 s77, s57, s1
	s_and_b64 s[0:1], s[38:39], exec
	s_cselect_b32 s8, s77, s41
	s_cselect_b32 s9, s76, s40
	s_add_u32 s10, s40, 0x100
	s_addc_u32 s12, s41, 0
	s_add_u32 s40, s48, 0x40080
	v_mov_b32_e32 v8, 0
	v_mov_b32_e32 v9, v8
	s_addc_u32 s41, s49, 0
	s_mov_b32 s13, -2
	v_mov_b64_e32 v[10:11], v[8:9]
	v_mov_b64_e32 v[12:13], v[8:9]
	v_mov_b64_e32 v[14:15], v[8:9]
	v_mov_b64_e32 v[24:25], v[8:9]
	v_mov_b64_e32 v[26:27], v[8:9]
	v_mov_b64_e32 v[28:29], v[8:9]
	v_mov_b64_e32 v[30:31], v[8:9]
	v_mov_b64_e32 v[40:41], v[8:9]
	v_mov_b64_e32 v[42:43], v[8:9]
	v_mov_b64_e32 v[44:45], v[8:9]
	v_mov_b64_e32 v[46:47], v[8:9]
	v_mov_b64_e32 v[56:57], v[8:9]
	v_mov_b64_e32 v[58:59], v[8:9]
	v_mov_b64_e32 v[60:61], v[8:9]
	v_mov_b64_e32 v[62:63], v[8:9]
	v_mov_b64_e32 v[0:1], v[8:9]
	v_mov_b64_e32 v[2:3], v[8:9]
	v_mov_b64_e32 v[4:5], v[8:9]
	v_mov_b64_e32 v[6:7], v[8:9]
	v_mov_b64_e32 v[16:17], v[8:9]
	v_mov_b64_e32 v[18:19], v[8:9]
	v_mov_b64_e32 v[20:21], v[8:9]
	v_mov_b64_e32 v[22:23], v[8:9]
	v_mov_b64_e32 v[32:33], v[8:9]
	v_mov_b64_e32 v[34:35], v[8:9]
	v_mov_b64_e32 v[36:37], v[8:9]
	v_mov_b64_e32 v[38:39], v[8:9]
	v_mov_b64_e32 v[48:49], v[8:9]
	v_mov_b64_e32 v[50:51], v[8:9]
	v_mov_b64_e32 v[52:53], v[8:9]
	v_mov_b64_e32 v[54:55], v[8:9]
	v_mov_b64_e32 v[72:73], v[8:9]
	v_mov_b64_e32 v[74:75], v[8:9]
	v_mov_b64_e32 v[76:77], v[8:9]
	v_mov_b64_e32 v[78:79], v[8:9]
	v_mov_b64_e32 v[88:89], v[8:9]
	v_mov_b64_e32 v[90:91], v[8:9]
	v_mov_b64_e32 v[92:93], v[8:9]
	v_mov_b64_e32 v[94:95], v[8:9]
	v_mov_b64_e32 v[104:105], v[8:9]
	v_mov_b64_e32 v[106:107], v[8:9]
	v_mov_b64_e32 v[108:109], v[8:9]
	v_mov_b64_e32 v[110:111], v[8:9]
	v_mov_b64_e32 v[120:121], v[8:9]
	v_mov_b64_e32 v[122:123], v[8:9]
	v_mov_b64_e32 v[124:125], v[8:9]
	v_mov_b64_e32 v[126:127], v[8:9]
	v_mov_b64_e32 v[64:65], v[8:9]
	v_mov_b64_e32 v[66:67], v[8:9]
	v_mov_b64_e32 v[68:69], v[8:9]
	v_mov_b64_e32 v[70:71], v[8:9]
	v_mov_b64_e32 v[80:81], v[8:9]
	v_mov_b64_e32 v[82:83], v[8:9]
	v_mov_b64_e32 v[84:85], v[8:9]
	v_mov_b64_e32 v[86:87], v[8:9]
	v_mov_b64_e32 v[96:97], v[8:9]
	v_mov_b64_e32 v[98:99], v[8:9]
	v_mov_b64_e32 v[100:101], v[8:9]
	v_mov_b64_e32 v[102:103], v[8:9]
	v_mov_b64_e32 v[112:113], v[8:9]
	v_mov_b64_e32 v[114:115], v[8:9]
	v_mov_b64_e32 v[116:117], v[8:9]
	v_mov_b64_e32 v[118:119], v[8:9]

; template <class Epi, class Sched, bool ALIGN_EPI = false, bool SP2 = false>
; __device__ __forceinline__ void gemm_phase(PG8_LAS unsigned char* lds, const Gemm g, const Sched& S, const Epi& E) {
;     ...
;         for (int a = 0; a < 2; ++a)
; #pragma unroll
;             for (int b = 0; b < 2; ++b)
; #pragma unroll
;                 for (int m = 0; m < 4; ++m)
; #pragma unroll
;                     for (int n = 0; n < 2; ++n) acc[a][b][m][n] = (f32x4){0.f, 0.f, 0.f, 0.f};
.LBB0_759:
	s_add_u32 s9, s48, 0x100
	v_mov_b32_e32 v0, 0
	v_mov_b32_e32 v1, v0
	s_addc_u32 s10, s49, 0
	s_mov_b32 s12, -2
	v_mov_b64_e32 v[2:3], v[0:1]
	v_mov_b64_e32 v[4:5], v[0:1]
	v_mov_b64_e32 v[6:7], v[0:1]
	v_mov_b64_e32 v[8:9], v[0:1]
	v_mov_b64_e32 v[10:11], v[0:1]
	v_mov_b64_e32 v[16:17], v[0:1]
	v_mov_b64_e32 v[18:19], v[0:1]
	v_mov_b64_e32 v[24:25], v[0:1]
	v_mov_b64_e32 v[26:27], v[0:1]
	v_mov_b64_e32 v[32:33], v[0:1]
	v_mov_b64_e32 v[34:35], v[0:1]
	v_mov_b64_e32 v[40:41], v[0:1]
	v_mov_b64_e32 v[42:43], v[0:1]
	v_mov_b64_e32 v[48:49], v[0:1]
	v_mov_b64_e32 v[50:51], v[0:1]
	v_mov_b64_e32 v[12:13], v[0:1]
	v_mov_b64_e32 v[14:15], v[0:1]
	v_mov_b64_e32 v[20:21], v[0:1]
	v_mov_b64_e32 v[22:23], v[0:1]
	v_mov_b64_e32 v[28:29], v[0:1]
	v_mov_b64_e32 v[30:31], v[0:1]
	v_mov_b64_e32 v[36:37], v[0:1]
	v_mov_b64_e32 v[38:39], v[0:1]
	v_mov_b64_e32 v[44:45], v[0:1]
	v_mov_b64_e32 v[46:47], v[0:1]
	v_mov_b64_e32 v[52:53], v[0:1]
	v_mov_b64_e32 v[54:55], v[0:1]
	v_mov_b64_e32 v[56:57], v[0:1]
	v_mov_b64_e32 v[58:59], v[0:1]
	v_mov_b64_e32 v[60:61], v[0:1]
	v_mov_b64_e32 v[62:63], v[0:1]
	v_mov_b64_e32 v[64:65], v[0:1]
	v_mov_b64_e32 v[66:67], v[0:1]
	v_mov_b64_e32 v[68:69], v[0:1]
	v_mov_b64_e32 v[70:71], v[0:1]
	v_mov_b64_e32 v[72:73], v[0:1]
	v_mov_b64_e32 v[74:75], v[0:1]
	v_mov_b64_e32 v[80:81], v[0:1]
	v_mov_b64_e32 v[82:83], v[0:1]
	v_mov_b64_e32 v[88:89], v[0:1]
	v_mov_b64_e32 v[90:91], v[0:1]
	v_mov_b64_e32 v[96:97], v[0:1]
	v_mov_b64_e32 v[98:99], v[0:1]
	v_mov_b64_e32 v[104:105], v[0:1]
	v_mov_b64_e32 v[106:107], v[0:1]
	v_mov_b64_e32 v[112:113], v[0:1]
	v_mov_b64_e32 v[114:115], v[0:1]
	v_mov_b64_e32 v[76:77], v[0:1]
	v_mov_b64_e32 v[78:79], v[0:1]
	v_mov_b64_e32 v[84:85], v[0:1]
	v_mov_b64_e32 v[86:87], v[0:1]
	v_mov_b64_e32 v[92:93], v[0:1]
	v_mov_b64_e32 v[94:95], v[0:1]
	v_mov_b64_e32 v[100:101], v[0:1]
	v_mov_b64_e32 v[102:103], v[0:1]
	v_mov_b64_e32 v[108:109], v[0:1]
	v_mov_b64_e32 v[110:111], v[0:1]
	v_mov_b64_e32 v[116:117], v[0:1]
	v_mov_b64_e32 v[118:119], v[0:1]
	v_mov_b64_e32 v[120:121], v[0:1]
	v_mov_b64_e32 v[122:123], v[0:1]
	v_mov_b64_e32 v[124:125], v[0:1]
	v_mov_b64_e32 v[126:127], v[0:1]

;     __host__ __device__ bool next(int i, Unit& u) const { const long L = (long)i * G + c; if (L >= nwg) return false; const int l = (int)L; u.ks = l % nS; const int t = l / nS; u.pn = t % nN; u.pm = t / nN; return true; }
; template <class Epi, class Sched, bool ALIGN_EPI = false, bool SP2 = false>
; __device__ __forceinline__ void gemm_phase(PG8_LAS unsigned char* lds, const Gemm g, const Sched& S, const Epi& E) {
;     ...
;         const bool has_next = S.next(ui + 1, nxt);
;         const char* nA = has_next ? (const char*)g.A + (size_t)nxt.pm * tstepA + (size_t)nxt.ks * ksl : cA; const char* nB = has_next ? (const char*)g.Bt + (size_t)nxt.pn * tstepB + (size_t)nxt.ks * ksl : cB;
;     ...
;         for (int a = 0; a < 2; ++a)
; #pragma unroll
;             for (int b = 0; b < 2; ++b)
; #pragma unroll
;                 for (int m = 0; m < 4; ++m)
; #pragma unroll
;                     for (int n = 0; n < 2; ++n) acc[a][b][m][n] = (f32x4){0.f, 0.f, 0.f, 0.f};
.LBB0_782:
	s_ashr_i32 s51, s50, 31
	s_lshl_b64 s[0:1], s[50:51], 17
	s_add_u32 s56, s79, s0
	s_addc_u32 s57, s78, s1
	s_and_b64 s[0:1], s[38:39], exec
	s_cselect_b32 s17, s57, s61
	s_cselect_b32 s51, s56, s60
	s_ashr_i32 s49, s48, 31
	s_lshl_b64 s[0:1], s[48:49], 17
	s_add_u32 s58, s12, s0
	s_addc_u32 s59, s94, s1
	s_and_b64 s[0:1], s[38:39], exec
	v_mov_b32_e32 v0, 0
	v_mov_b32_e32 v1, v0
	s_cselect_b32 s49, s59, s55
	s_cselect_b32 s30, s58, s54
	s_mov_b32 s0, 0
	s_mov_b64 s[62:63], -1
	s_mov_b64 s[64:65], 0
	v_mov_b64_e32 v[2:3], v[0:1]
	v_mov_b64_e32 v[4:5], v[0:1]
	v_mov_b64_e32 v[6:7], v[0:1]
	v_mov_b64_e32 v[8:9], v[0:1]
	v_mov_b64_e32 v[10:11], v[0:1]
	v_mov_b64_e32 v[12:13], v[0:1]
	v_mov_b64_e32 v[14:15], v[0:1]
	v_mov_b64_e32 v[24:25], v[0:1]
	v_mov_b64_e32 v[26:27], v[0:1]
	v_mov_b64_e32 v[28:29], v[0:1]
	v_mov_b64_e32 v[30:31], v[0:1]
	v_mov_b64_e32 v[40:41], v[0:1]
	v_mov_b64_e32 v[42:43], v[0:1]
	v_mov_b64_e32 v[44:45], v[0:1]
	v_mov_b64_e32 v[46:47], v[0:1]
	v_mov_b64_e32 v[16:17], v[0:1]
	v_mov_b64_e32 v[18:19], v[0:1]
	v_mov_b64_e32 v[20:21], v[0:1]
	v_mov_b64_e32 v[22:23], v[0:1]
	v_mov_b64_e32 v[32:33], v[0:1]
	v_mov_b64_e32 v[34:35], v[0:1]
	v_mov_b64_e32 v[36:37], v[0:1]
	v_mov_b64_e32 v[38:39], v[0:1]
	v_mov_b64_e32 v[48:49], v[0:1]
	v_mov_b64_e32 v[50:51], v[0:1]
	v_mov_b64_e32 v[52:53], v[0:1]
	v_mov_b64_e32 v[54:55], v[0:1]
	v_mov_b64_e32 v[56:57], v[0:1]
	v_mov_b64_e32 v[58:59], v[0:1]
	v_mov_b64_e32 v[60:61], v[0:1]
	v_mov_b64_e32 v[62:63], v[0:1]
	v_mov_b64_e32 v[64:65], v[0:1]
	v_mov_b64_e32 v[66:67], v[0:1]
	v_mov_b64_e32 v[68:69], v[0:1]
	v_mov_b64_e32 v[70:71], v[0:1]
	v_mov_b64_e32 v[72:73], v[0:1]
	v_mov_b64_e32 v[74:75], v[0:1]
	v_mov_b64_e32 v[76:77], v[0:1]
	v_mov_b64_e32 v[78:79], v[0:1]
	v_mov_b64_e32 v[88:89], v[0:1]
	v_mov_b64_e32 v[90:91], v[0:1]
	v_mov_b64_e32 v[92:93], v[0:1]
	v_mov_b64_e32 v[94:95], v[0:1]
	v_mov_b64_e32 v[104:105], v[0:1]
	v_mov_b64_e32 v[106:107], v[0:1]
	v_mov_b64_e32 v[108:109], v[0:1]
	v_mov_b64_e32 v[110:111], v[0:1]
	v_mov_b64_e32 v[80:81], v[0:1]
	v_mov_b64_e32 v[82:83], v[0:1]
	v_mov_b64_e32 v[84:85], v[0:1]
	v_mov_b64_e32 v[86:87], v[0:1]
	v_mov_b64_e32 v[96:97], v[0:1]
	v_mov_b64_e32 v[98:99], v[0:1]
	v_mov_b64_e32 v[100:101], v[0:1]
	v_mov_b64_e32 v[102:103], v[0:1]
	v_mov_b64_e32 v[112:113], v[0:1]
	v_mov_b64_e32 v[114:115], v[0:1]
	v_mov_b64_e32 v[116:117], v[0:1]
	v_mov_b64_e32 v[118:119], v[0:1]
	v_mov_b64_e32 v[120:121], v[0:1]
	v_mov_b64_e32 v[122:123], v[0:1]
	v_mov_b64_e32 v[124:125], v[0:1]
	v_mov_b64_e32 v[126:127], v[0:1]

; __global__ void __launch_bounds__(NWAVES * 64, 2) mega_fwd(Args a) {
;     ...
;                   const int round = i >> 8, cu = i & 255, p = cu >> 1, odd = cu & 1, bl = p >> 3, h = p & 7;
;                   const int qb = odd ? (round == 0 ? 7 : round == 1 ? 5 : round == 2 ? 0 : -1) : (round == 0 ? 6 : round == 1 ? 4 : round == 2 ? 3 : round == 3 ? 2 : 1);
;                   if (qb >= 0) att::unit(lds, T, h, bl * SEQ + qb * 256, 8, false, 4 * qb, bl * SEQ, 0, 4 * qb + 4);
.LBB0_850:
	s_ashr_i32 s8, s47, 8
	s_and_b32 s0, s47, 1
	s_cmpk_gt_u32 s47, 0xff
	s_cselect_b64 s[2:3], -1, 0
	v_cndmask_b32_e64 v0, 0, 1, s[2:3]
	s_cmp_eq_u32 s0, 0
	s_mov_b64 s[0:1], -1
	v_cmp_ne_u32_e64 s[38:39], 1, v0
	s_cbranch_scc1 .LBB0_854
	s_and_b64 vcc, exec, s[38:39]
	s_mov_b32 s27, 7
	s_cbranch_vccnz .LBB0_853
	s_cmp_lg_u32 s8, 2
	s_cselect_b64 s[0:1], -1, 0
	v_cndmask_b32_e64 v0, 1, -1, s[0:1]
	s_cmp_lg_u32 s8, 1
	v_readfirstlane_b32 s0, v0
	s_cselect_b32 s27, s0, 5

; __global__ void __launch_bounds__(NWAVES * 64, 2) mega_fwd(Args a) {
;     ...
;                   const int qb = odd ? (round == 0 ? 7 : round == 1 ? 5 : round == 2 ? 0 : -1) : (round == 0 ? 6 : round == 1 ? 4 : round == 2 ? 3 : round == 3 ? 2 : 1);
.LBB0_862:
	s_andn2_b64 vcc, exec, s[0:1]
	s_cbranch_vccnz .LBB0_864
	s_cmp_eq_u32 s8, 3
	s_cselect_b32 s27, 2, 0

;     __host__ __device__ bool next(int i, Unit& u) const { const long L = (long)i * G + c; if (L >= nwg) return false; const int l = (int)L; u.ks = l % nS; const int t = l / nS; u.pn = t % nN; u.pm = t / nN; return true; }
; template <class Epi, class Sched, bool ALIGN_EPI = false, bool SP2 = false>
; __device__ __forceinline__ void gemm_phase(PG8_LAS unsigned char* lds, const Gemm g, const Sched& S, const Epi& E) {
;     ...
;         const bool has_next = S.next(ui + 1, nxt);
;         const char* nA = has_next ? (const char*)g.A + (size_t)nxt.pm * tstepA + (size_t)nxt.ks * ksl : cA; const char* nB = has_next ? (const char*)g.Bt + (size_t)nxt.pn * tstepB + (size_t)nxt.ks * ksl : cB;
;     ...
;         for (int a = 0; a < 2; ++a)
; #pragma unroll
;             for (int b = 0; b < 2; ++b)
; #pragma unroll
;                 for (int m = 0; m < 4; ++m)
; #pragma unroll
;                     for (int n = 0; n < 2; ++n) acc[a][b][m][n] = (f32x4){0.f, 0.f, 0.f, 0.f};
.LBB0_1026:
	s_ashr_i32 s51, s50, 31
	s_lshl_b64 s[0:1], s[50:51], 19
	s_add_u32 s52, s3, s0
	s_addc_u32 s53, s12, s1
	s_and_b64 s[0:1], s[38:39], exec
	s_cselect_b32 s16, s53, s59
	s_cselect_b32 s17, s52, s58
	s_ashr_i32 s49, s48, 31
	s_lshl_b64 s[0:1], s[48:49], 19
	s_add_u32 s54, s28, s0
	s_addc_u32 s55, s29, s1
	s_and_b64 s[0:1], s[38:39], exec
	s_cselect_b32 s49, s55, s57
	s_cselect_b32 s51, s54, s56
	s_add_u32 s61, s56, 0x100
	s_addc_u32 s62, s57, 0
	s_add_u32 s56, s58, 0x40080
	v_mov_b32_e32 v0, 0
	v_mov_b32_e32 v1, v0
	s_addc_u32 s57, s59, 0
	s_mov_b32 s63, -2
	v_mov_b64_e32 v[2:3], v[0:1]
	v_mov_b64_e32 v[4:5], v[0:1]
	v_mov_b64_e32 v[6:7], v[0:1]
	v_mov_b64_e32 v[8:9], v[0:1]
	v_mov_b64_e32 v[10:11], v[0:1]
	v_mov_b64_e32 v[12:13], v[0:1]
	v_mov_b64_e32 v[14:15], v[0:1]
	v_mov_b64_e32 v[24:25], v[0:1]
	v_mov_b64_e32 v[26:27], v[0:1]
	v_mov_b64_e32 v[28:29], v[0:1]
	v_mov_b64_e32 v[30:31], v[0:1]
	v_mov_b64_e32 v[40:41], v[0:1]
	v_mov_b64_e32 v[42:43], v[0:1]
	v_mov_b64_e32 v[44:45], v[0:1]
	v_mov_b64_e32 v[46:47], v[0:1]
	v_mov_b64_e32 v[16:17], v[0:1]
	v_mov_b64_e32 v[18:19], v[0:1]
	v_mov_b64_e32 v[20:21], v[0:1]
	v_mov_b64_e32 v[22:23], v[0:1]
	v_mov_b64_e32 v[32:33], v[0:1]
	v_mov_b64_e32 v[34:35], v[0:1]
	v_mov_b64_e32 v[36:37], v[0:1]
	v_mov_b64_e32 v[38:39], v[0:1]
	v_mov_b64_e32 v[48:49], v[0:1]
	v_mov_b64_e32 v[50:51], v[0:1]
	v_mov_b64_e32 v[52:53], v[0:1]
	v_mov_b64_e32 v[54:55], v[0:1]
	v_mov_b64_e32 v[56:57], v[0:1]
	v_mov_b64_e32 v[58:59], v[0:1]
	v_mov_b64_e32 v[60:61], v[0:1]
	v_mov_b64_e32 v[62:63], v[0:1]
	v_mov_b64_e32 v[64:65], v[0:1]
	v_mov_b64_e32 v[66:67], v[0:1]
	v_mov_b64_e32 v[68:69], v[0:1]
	v_mov_b64_e32 v[70:71], v[0:1]
	v_mov_b64_e32 v[72:73], v[0:1]
	v_mov_b64_e32 v[74:75], v[0:1]
	v_mov_b64_e32 v[76:77], v[0:1]
	v_mov_b64_e32 v[78:79], v[0:1]
	v_mov_b64_e32 v[88:89], v[0:1]
	v_mov_b64_e32 v[90:91], v[0:1]
	v_mov_b64_e32 v[92:93], v[0:1]
	v_mov_b64_e32 v[94:95], v[0:1]
	v_mov_b64_e32 v[104:105], v[0:1]
	v_mov_b64_e32 v[106:107], v[0:1]
	v_mov_b64_e32 v[108:109], v[0:1]
	v_mov_b64_e32 v[110:111], v[0:1]
	v_mov_b64_e32 v[80:81], v[0:1]
	v_mov_b64_e32 v[82:83], v[0:1]
	v_mov_b64_e32 v[84:85], v[0:1]
	v_mov_b64_e32 v[86:87], v[0:1]
	v_mov_b64_e32 v[96:97], v[0:1]
	v_mov_b64_e32 v[98:99], v[0:1]
	v_mov_b64_e32 v[100:101], v[0:1]
	v_mov_b64_e32 v[102:103], v[0:1]
	v_mov_b64_e32 v[112:113], v[0:1]
	v_mov_b64_e32 v[114:115], v[0:1]
	v_mov_b64_e32 v[116:117], v[0:1]
	v_mov_b64_e32 v[118:119], v[0:1]
	v_mov_b64_e32 v[120:121], v[0:1]
	v_mov_b64_e32 v[122:123], v[0:1]
	v_mov_b64_e32 v[124:125], v[0:1]
	v_mov_b64_e32 v[126:127], v[0:1]

; template <class Epi, class Sched, bool ALIGN_EPI = false, bool SP2 = false>
; __device__ __forceinline__ void gemm_phase(PG8_LAS unsigned char* lds, const Gemm g, const Sched& S, const Epi& E) {
;     ...
;         for (int a = 0; a < 2; ++a)
; #pragma unroll
;             for (int b = 0; b < 2; ++b)
; #pragma unroll
;                 for (int m = 0; m < 4; ++m)
; #pragma unroll
;                     for (int n = 0; n < 2; ++n) acc[a][b][m][n] = (f32x4){0.f, 0.f, 0.f, 0.f};
.LBB0_1046:
	v_mov_b32_e32 v0, 0
	v_mov_b32_e32 v1, v0
	s_mov_b32 s0, 0
	s_mov_b64 s[62:63], -1
	s_mov_b64 s[64:65], 0
	v_mov_b64_e32 v[2:3], v[0:1]
	v_mov_b64_e32 v[4:5], v[0:1]
	v_mov_b64_e32 v[6:7], v[0:1]
	v_mov_b64_e32 v[8:9], v[0:1]
	v_mov_b64_e32 v[10:11], v[0:1]
	v_mov_b64_e32 v[12:13], v[0:1]
	v_mov_b64_e32 v[14:15], v[0:1]
	v_mov_b64_e32 v[20:21], v[0:1]
	v_mov_b64_e32 v[22:23], v[0:1]
	v_mov_b64_e32 v[28:29], v[0:1]
	v_mov_b64_e32 v[30:31], v[0:1]
	v_mov_b64_e32 v[36:37], v[0:1]
	v_mov_b64_e32 v[38:39], v[0:1]
	v_mov_b64_e32 v[44:45], v[0:1]
	v_mov_b64_e32 v[46:47], v[0:1]
	v_mov_b64_e32 v[16:17], v[0:1]
	v_mov_b64_e32 v[18:19], v[0:1]
	v_mov_b64_e32 v[24:25], v[0:1]
	v_mov_b64_e32 v[26:27], v[0:1]
	v_mov_b64_e32 v[32:33], v[0:1]
	v_mov_b64_e32 v[34:35], v[0:1]
	v_mov_b64_e32 v[40:41], v[0:1]
	v_mov_b64_e32 v[42:43], v[0:1]
	v_mov_b64_e32 v[48:49], v[0:1]
	v_mov_b64_e32 v[50:51], v[0:1]
	v_mov_b64_e32 v[52:53], v[0:1]
	v_mov_b64_e32 v[54:55], v[0:1]
	v_mov_b64_e32 v[56:57], v[0:1]
	v_mov_b64_e32 v[58:59], v[0:1]
	v_mov_b64_e32 v[60:61], v[0:1]
	v_mov_b64_e32 v[62:63], v[0:1]
	v_mov_b64_e32 v[64:65], v[0:1]
	v_mov_b64_e32 v[66:67], v[0:1]
	v_mov_b64_e32 v[68:69], v[0:1]
	v_mov_b64_e32 v[70:71], v[0:1]
	v_mov_b64_e32 v[72:73], v[0:1]
	v_mov_b64_e32 v[74:75], v[0:1]
	v_mov_b64_e32 v[76:77], v[0:1]
	v_mov_b64_e32 v[78:79], v[0:1]
	v_mov_b64_e32 v[80:81], v[0:1]
	v_mov_b64_e32 v[82:83], v[0:1]
	v_mov_b64_e32 v[88:89], v[0:1]
	v_mov_b64_e32 v[90:91], v[0:1]
	v_mov_b64_e32 v[96:97], v[0:1]
	v_mov_b64_e32 v[98:99], v[0:1]
	v_mov_b64_e32 v[104:105], v[0:1]
	v_mov_b64_e32 v[106:107], v[0:1]
	v_mov_b64_e32 v[84:85], v[0:1]
	v_mov_b64_e32 v[86:87], v[0:1]
	v_mov_b64_e32 v[92:93], v[0:1]
	v_mov_b64_e32 v[94:95], v[0:1]
	v_mov_b64_e32 v[100:101], v[0:1]
	v_mov_b64_e32 v[102:103], v[0:1]
	v_mov_b64_e32 v[108:109], v[0:1]
	v_mov_b64_e32 v[110:111], v[0:1]
	v_mov_b64_e32 v[112:113], v[0:1]
	v_mov_b64_e32 v[114:115], v[0:1]
	v_mov_b64_e32 v[116:117], v[0:1]
	v_mov_b64_e32 v[118:119], v[0:1]
	v_mov_b64_e32 v[120:121], v[0:1]
	v_mov_b64_e32 v[122:123], v[0:1]
	v_mov_b64_e32 v[124:125], v[0:1]
	v_mov_b64_e32 v[126:127], v[0:1]

;     __host__ __device__ bool next(int i, Unit& u) const { const long L = (long)i * G + c; if (L >= nwg) return false; const int l = (int)L; u.ks = l % nS; const int t = l / nS; u.pn = t % nN; u.pm = t / nN; return true; }
; template <class Epi, class Sched, bool ALIGN_EPI = false, bool SP2 = false>
; __device__ __forceinline__ void gemm_phase(PG8_LAS unsigned char* lds, const Gemm g, const Sched& S, const Epi& E) {
;     ...
;         const bool has_next = S.next(ui + 1, nxt);
;         const char* nA = has_next ? (const char*)g.A + (size_t)nxt.pm * tstepA + (size_t)nxt.ks * ksl : cA; const char* nB = has_next ? (const char*)g.Bt + (size_t)nxt.pn * tstepB + (size_t)nxt.ks * ksl : cB;
;     ...
;         for (int a = 0; a < 2; ++a)
; #pragma unroll
;             for (int b = 0; b < 2; ++b)
; #pragma unroll
;                 for (int m = 0; m < 4; ++m)
; #pragma unroll
;                     for (int n = 0; n < 2; ++n) acc[a][b][m][n] = (f32x4){0.f, 0.f, 0.f, 0.f};
.LBB0_1217:
	s_ashr_i32 s67, s66, 31
	s_lshl_b64 s[0:1], s[66:67], 19
	s_add_u32 s68, s46, s0
	s_addc_u32 s69, s47, s1
	s_and_b64 s[0:1], s[38:39], exec
	s_cselect_b32 s9, s69, s51
	s_cselect_b32 s10, s68, s50
	s_ashr_i32 s65, s64, 31
	s_lshl_b64 s[0:1], s[64:65], 19
	s_add_u32 s70, s52, s0
	s_addc_u32 s71, s53, s1
	s_and_b64 s[0:1], s[38:39], exec
	s_cselect_b32 s12, s71, s49
	s_cselect_b32 s13, s70, s48
	s_add_u32 s16, s48, 0x100
	s_addc_u32 s17, s49, 0
	s_add_u32 s48, s50, 0x40080
	v_mov_b32_e32 v0, 0
	v_mov_b32_e32 v1, v0
	s_addc_u32 s49, s51, 0
	s_mov_b32 s18, -2
	v_mov_b64_e32 v[2:3], v[0:1]
	v_mov_b64_e32 v[4:5], v[0:1]
	v_mov_b64_e32 v[6:7], v[0:1]
	v_mov_b64_e32 v[16:17], v[0:1]
	v_mov_b64_e32 v[18:19], v[0:1]
	v_mov_b64_e32 v[20:21], v[0:1]
	v_mov_b64_e32 v[22:23], v[0:1]
	v_mov_b64_e32 v[32:33], v[0:1]
	v_mov_b64_e32 v[34:35], v[0:1]
	v_mov_b64_e32 v[36:37], v[0:1]
	v_mov_b64_e32 v[38:39], v[0:1]
	v_mov_b64_e32 v[48:49], v[0:1]
	v_mov_b64_e32 v[50:51], v[0:1]
	v_mov_b64_e32 v[52:53], v[0:1]
	v_mov_b64_e32 v[54:55], v[0:1]
	v_mov_b64_e32 v[8:9], v[0:1]
	v_mov_b64_e32 v[10:11], v[0:1]
	v_mov_b64_e32 v[12:13], v[0:1]
	v_mov_b64_e32 v[14:15], v[0:1]
	v_mov_b64_e32 v[24:25], v[0:1]
	v_mov_b64_e32 v[26:27], v[0:1]
	v_mov_b64_e32 v[28:29], v[0:1]
	v_mov_b64_e32 v[30:31], v[0:1]
	v_mov_b64_e32 v[40:41], v[0:1]
	v_mov_b64_e32 v[42:43], v[0:1]
	v_mov_b64_e32 v[44:45], v[0:1]
	v_mov_b64_e32 v[46:47], v[0:1]
	v_mov_b64_e32 v[56:57], v[0:1]
	v_mov_b64_e32 v[58:59], v[0:1]
	v_mov_b64_e32 v[60:61], v[0:1]
	v_mov_b64_e32 v[62:63], v[0:1]
	v_mov_b64_e32 v[64:65], v[0:1]
	v_mov_b64_e32 v[66:67], v[0:1]
	v_mov_b64_e32 v[68:69], v[0:1]
	v_mov_b64_e32 v[70:71], v[0:1]
	v_mov_b64_e32 v[80:81], v[0:1]
	v_mov_b64_e32 v[82:83], v[0:1]
	v_mov_b64_e32 v[84:85], v[0:1]
	v_mov_b64_e32 v[86:87], v[0:1]
	v_mov_b64_e32 v[96:97], v[0:1]
	v_mov_b64_e32 v[98:99], v[0:1]
	v_mov_b64_e32 v[100:101], v[0:1]
	v_mov_b64_e32 v[102:103], v[0:1]
	v_mov_b64_e32 v[112:113], v[0:1]
	v_mov_b64_e32 v[114:115], v[0:1]
	v_mov_b64_e32 v[116:117], v[0:1]
	v_mov_b64_e32 v[118:119], v[0:1]
	v_mov_b64_e32 v[72:73], v[0:1]
	v_mov_b64_e32 v[74:75], v[0:1]
	v_mov_b64_e32 v[76:77], v[0:1]
	v_mov_b64_e32 v[78:79], v[0:1]
	v_mov_b64_e32 v[88:89], v[0:1]
	v_mov_b64_e32 v[90:91], v[0:1]
	v_mov_b64_e32 v[92:93], v[0:1]
	v_mov_b64_e32 v[94:95], v[0:1]
	v_mov_b64_e32 v[104:105], v[0:1]
	v_mov_b64_e32 v[106:107], v[0:1]
	v_mov_b64_e32 v[108:109], v[0:1]
	v_mov_b64_e32 v[110:111], v[0:1]
	v_mov_b64_e32 v[120:121], v[0:1]
	v_mov_b64_e32 v[122:123], v[0:1]
	v_mov_b64_e32 v[124:125], v[0:1]
	v_mov_b64_e32 v[126:127], v[0:1]

;     __host__ __device__ bool next(int i, Unit& u) const { const long L = (long)i * G + c; if (L >= nwg) return false; const int l = (int)L; u.ks = l % nS; const int t = l / nS; u.pn = t % nN; u.pm = t / nN; return true; }
; template <class Epi, class Sched, bool ALIGN_EPI = false, bool SP2 = false>
; __device__ __forceinline__ void gemm_phase(PG8_LAS unsigned char* lds, const Gemm g, const Sched& S, const Epi& E) {
;     ...
;         const bool has_next = S.next(ui + 1, nxt);
;         const char* nA = has_next ? (const char*)g.A + (size_t)nxt.pm * tstepA + (size_t)nxt.ks * ksl : cA; const char* nB = has_next ? (const char*)g.Bt + (size_t)nxt.pn * tstepB + (size_t)nxt.ks * ksl : cB;
;     ...
;         for (int a = 0; a < 2; ++a)
; #pragma unroll
;             for (int b = 0; b < 2; ++b)
; #pragma unroll
;                 for (int m = 0; m < 4; ++m)
; #pragma unroll
;                     for (int n = 0; n < 2; ++n) acc[a][b][m][n] = (f32x4){0.f, 0.f, 0.f, 0.f};
.LBB0_1296:
	s_ashr_i32 s51, s50, 31
	s_lshl_b64 s[0:1], s[50:51], 21
	s_add_u32 s52, s12, s0
	s_addc_u32 s53, s13, s1
	s_and_b64 s[0:1], s[38:39], exec
	s_cselect_b32 s16, s53, s59
	s_cselect_b32 s17, s52, s58
	s_ashr_i32 s49, s48, 31
	s_lshl_b64 s[0:1], s[48:49], 21
	s_add_u32 s54, s26, s0
	s_addc_u32 s55, s27, s1
	s_and_b64 s[0:1], s[38:39], exec
	s_cselect_b32 s49, s55, s57
	s_cselect_b32 s51, s54, s56
	s_add_u32 s61, s56, 0x100
	s_addc_u32 s62, s57, 0
	s_add_u32 s56, s58, 0x100080
	v_mov_b32_e32 v0, 0
	v_mov_b32_e32 v1, v0
	s_addc_u32 s57, s59, 0
	s_mov_b32 s63, -2
	v_mov_b64_e32 v[2:3], v[0:1]
	v_mov_b64_e32 v[4:5], v[0:1]
	v_mov_b64_e32 v[6:7], v[0:1]
	v_mov_b64_e32 v[8:9], v[0:1]
	v_mov_b64_e32 v[10:11], v[0:1]
	v_mov_b64_e32 v[12:13], v[0:1]
	v_mov_b64_e32 v[14:15], v[0:1]
	v_mov_b64_e32 v[24:25], v[0:1]
	v_mov_b64_e32 v[26:27], v[0:1]
	v_mov_b64_e32 v[28:29], v[0:1]
	v_mov_b64_e32 v[30:31], v[0:1]
	v_mov_b64_e32 v[40:41], v[0:1]
	v_mov_b64_e32 v[42:43], v[0:1]
	v_mov_b64_e32 v[44:45], v[0:1]
	v_mov_b64_e32 v[46:47], v[0:1]
	v_mov_b64_e32 v[16:17], v[0:1]
	v_mov_b64_e32 v[18:19], v[0:1]
	v_mov_b64_e32 v[20:21], v[0:1]
	v_mov_b64_e32 v[22:23], v[0:1]
	v_mov_b64_e32 v[32:33], v[0:1]
	v_mov_b64_e32 v[34:35], v[0:1]
	v_mov_b64_e32 v[36:37], v[0:1]
	v_mov_b64_e32 v[38:39], v[0:1]
	v_mov_b64_e32 v[48:49], v[0:1]
	v_mov_b64_e32 v[50:51], v[0:1]
	v_mov_b64_e32 v[52:53], v[0:1]
	v_mov_b64_e32 v[54:55], v[0:1]
	v_mov_b64_e32 v[56:57], v[0:1]
	v_mov_b64_e32 v[58:59], v[0:1]
	v_mov_b64_e32 v[60:61], v[0:1]
	v_mov_b64_e32 v[62:63], v[0:1]
	v_mov_b64_e32 v[64:65], v[0:1]
	v_mov_b64_e32 v[66:67], v[0:1]
	v_mov_b64_e32 v[68:69], v[0:1]
	v_mov_b64_e32 v[70:71], v[0:1]
	v_mov_b64_e32 v[72:73], v[0:1]
	v_mov_b64_e32 v[74:75], v[0:1]
	v_mov_b64_e32 v[76:77], v[0:1]
	v_mov_b64_e32 v[78:79], v[0:1]
	v_mov_b64_e32 v[88:89], v[0:1]
	v_mov_b64_e32 v[90:91], v[0:1]
	v_mov_b64_e32 v[92:93], v[0:1]
	v_mov_b64_e32 v[94:95], v[0:1]
	v_mov_b64_e32 v[104:105], v[0:1]
	v_mov_b64_e32 v[106:107], v[0:1]
	v_mov_b64_e32 v[108:109], v[0:1]
	v_mov_b64_e32 v[110:111], v[0:1]
	v_mov_b64_e32 v[80:81], v[0:1]
	v_mov_b64_e32 v[82:83], v[0:1]
	v_mov_b64_e32 v[84:85], v[0:1]
	v_mov_b64_e32 v[86:87], v[0:1]
	v_mov_b64_e32 v[96:97], v[0:1]
	v_mov_b64_e32 v[98:99], v[0:1]
	v_mov_b64_e32 v[100:101], v[0:1]
	v_mov_b64_e32 v[102:103], v[0:1]
	v_mov_b64_e32 v[112:113], v[0:1]
	v_mov_b64_e32 v[114:115], v[0:1]
	v_mov_b64_e32 v[116:117], v[0:1]
	v_mov_b64_e32 v[118:119], v[0:1]
	v_mov_b64_e32 v[120:121], v[0:1]
	v_mov_b64_e32 v[122:123], v[0:1]
	v_mov_b64_e32 v[124:125], v[0:1]
	v_mov_b64_e32 v[126:127], v[0:1]

; template <class Epi, class Sched, bool ALIGN_EPI = false, bool SP2 = false>
; __device__ __forceinline__ void gemm_phase(PG8_LAS unsigned char* lds, const Gemm g, const Sched& S, const Epi& E) {
;     ...
;         for (int a = 0; a < 2; ++a)
; #pragma unroll
;             for (int b = 0; b < 2; ++b)
; #pragma unroll
;                 for (int m = 0; m < 4; ++m)
; #pragma unroll
;                     for (int n = 0; n < 2; ++n) acc[a][b][m][n] = (f32x4){0.f, 0.f, 0.f, 0.f};
.LBB0_1316:
	s_add_u32 s16, s58, 0x100
	s_addc_u32 s17, s59, 0
	s_add_u32 s58, s60, 0x100080
	v_mov_b32_e32 v0, 0
	v_mov_b32_e32 v1, v0
	s_addc_u32 s59, s61, 0
	s_mov_b32 s43, -2
	v_mov_b64_e32 v[2:3], v[0:1]
	v_mov_b64_e32 v[4:5], v[0:1]
	v_mov_b64_e32 v[6:7], v[0:1]
	v_mov_b64_e32 v[8:9], v[0:1]
	v_mov_b64_e32 v[10:11], v[0:1]
	v_mov_b64_e32 v[12:13], v[0:1]
	v_mov_b64_e32 v[14:15], v[0:1]
	v_mov_b64_e32 v[20:21], v[0:1]
	v_mov_b64_e32 v[22:23], v[0:1]
	v_mov_b64_e32 v[28:29], v[0:1]
	v_mov_b64_e32 v[30:31], v[0:1]
	v_mov_b64_e32 v[36:37], v[0:1]
	v_mov_b64_e32 v[38:39], v[0:1]
	v_mov_b64_e32 v[44:45], v[0:1]
	v_mov_b64_e32 v[46:47], v[0:1]
	v_mov_b64_e32 v[16:17], v[0:1]
	v_mov_b64_e32 v[18:19], v[0:1]
	v_mov_b64_e32 v[24:25], v[0:1]
	v_mov_b64_e32 v[26:27], v[0:1]
	v_mov_b64_e32 v[32:33], v[0:1]
	v_mov_b64_e32 v[34:35], v[0:1]
	v_mov_b64_e32 v[40:41], v[0:1]
	v_mov_b64_e32 v[42:43], v[0:1]
	v_mov_b64_e32 v[48:49], v[0:1]
	v_mov_b64_e32 v[50:51], v[0:1]
	v_mov_b64_e32 v[52:53], v[0:1]
	v_mov_b64_e32 v[54:55], v[0:1]
	v_mov_b64_e32 v[56:57], v[0:1]
	v_mov_b64_e32 v[58:59], v[0:1]
	v_mov_b64_e32 v[60:61], v[0:1]
	v_mov_b64_e32 v[62:63], v[0:1]
	v_mov_b64_e32 v[64:65], v[0:1]
	v_mov_b64_e32 v[66:67], v[0:1]
	v_mov_b64_e32 v[68:69], v[0:1]
	v_mov_b64_e32 v[70:71], v[0:1]
	v_mov_b64_e32 v[72:73], v[0:1]
	v_mov_b64_e32 v[74:75], v[0:1]
	v_mov_b64_e32 v[76:77], v[0:1]
	v_mov_b64_e32 v[78:79], v[0:1]
	v_mov_b64_e32 v[80:81], v[0:1]
	v_mov_b64_e32 v[82:83], v[0:1]
	v_mov_b64_e32 v[88:89], v[0:1]
	v_mov_b64_e32 v[90:91], v[0:1]
	v_mov_b64_e32 v[96:97], v[0:1]
	v_mov_b64_e32 v[98:99], v[0:1]
	v_mov_b64_e32 v[104:105], v[0:1]
	v_mov_b64_e32 v[106:107], v[0:1]
	v_mov_b64_e32 v[84:85], v[0:1]
	v_mov_b64_e32 v[86:87], v[0:1]
	v_mov_b64_e32 v[92:93], v[0:1]
	v_mov_b64_e32 v[94:95], v[0:1]
	v_mov_b64_e32 v[100:101], v[0:1]
	v_mov_b64_e32 v[102:103], v[0:1]
	v_mov_b64_e32 v[108:109], v[0:1]
	v_mov_b64_e32 v[110:111], v[0:1]
	v_mov_b64_e32 v[112:113], v[0:1]
	v_mov_b64_e32 v[114:115], v[0:1]
	v_mov_b64_e32 v[116:117], v[0:1]
	v_mov_b64_e32 v[118:119], v[0:1]
	v_mov_b64_e32 v[120:121], v[0:1]
	v_mov_b64_e32 v[122:123], v[0:1]
	v_mov_b64_e32 v[124:125], v[0:1]
	v_mov_b64_e32 v[126:127], v[0:1]
